# grid barrier: every non-leader workgroup also issues an asynchronous buffer_wbl2 on arrival so the XCD L2 is written back progressively instead of only by the last arriver
# baseline (speedup 1.0000x reference)
.LBB0_259:
	s_lshl_b32 s4, s97, 8
	s_add_u32 s4, s78, s4
	s_addc_u32 s5, s79, 0
	v_mov_b32_e32 v3, 0x1000
	v_mov_b32_e32 v5, 1
	global_atomic_add v5, v3, v5, s[4:5] offset:1024 sc0
	v_cvt_f32_u32_e32 v3, v4
	v_sub_u32_e32 v6, 0, v4
	v_rcp_iflag_f32_e32 v3, v3
	s_nop 0
	v_mul_f32_e32 v3, 0x4f7ffffe, v3
	v_cvt_u32_f32_e32 v3, v3
	v_mul_lo_u32 v6, v6, v3
	v_mul_hi_u32 v6, v3, v6
	v_add_u32_e32 v3, v3, v6
	s_waitcnt vmcnt(0)
	v_mul_hi_u32 v3, v5, v3
	v_mul_lo_u32 v6, v3, v4
	v_sub_u32_e32 v6, v5, v6
	v_add_u32_e32 v7, 1, v3
	v_cmp_ge_u32_e32 vcc, v6, v4
	v_add_u32_e32 v5, 1, v5
	s_nop 0
	v_cndmask_b32_e32 v3, v3, v7, vcc
	v_sub_u32_e32 v7, v6, v4
	v_cndmask_b32_e32 v6, v6, v7, vcc
	v_add_u32_e32 v7, 1, v3
	v_cmp_ge_u32_e32 vcc, v6, v4
	s_nop 1
	v_cndmask_b32_e32 v3, v3, v7, vcc
	v_mul_lo_u32 v6, v4, v3
	v_add_u32_e32 v4, v6, v4
	v_cmp_ne_u32_e32 vcc, v5, v4
	s_and_saveexec_b64 s[6:7], vcc
	s_xor_b64 s[6:7], exec, s[6:7]
	s_cbranch_execz .LBB0_273
	s_waitcnt lgkmcnt(0)
	buffer_wbl2 sc1
	v_mov_b32_e32 v2, 0x2000
	global_load_dword v2, v2, s[4:5] offset:1024 sc1
	s_add_u32 s12, s4, 0x2400
	s_addc_u32 s13, s5, 0
	s_waitcnt vmcnt(0)
	v_cmp_eq_u32_e32 vcc, v2, v3
	s_and_saveexec_b64 s[10:11], vcc
	s_cbranch_execz .LBB0_272
	s_mov_b32 s30, 1
	s_mov_b64 s[16:17], 0
	v_mov_b32_e32 v2, 0
	s_branch .LBB0_263

.LBB0_354:
	s_lshl_b32 s4, s97, 8
	s_add_u32 s4, s78, s4
	s_addc_u32 s5, s79, 0
	v_mov_b32_e32 v3, 0x1000
	v_mov_b32_e32 v5, 1
	global_atomic_add v5, v3, v5, s[4:5] offset:1024 sc0
	v_cvt_f32_u32_e32 v3, v4
	v_sub_u32_e32 v6, 0, v4
	v_rcp_iflag_f32_e32 v3, v3
	s_nop 0
	v_mul_f32_e32 v3, 0x4f7ffffe, v3
	v_cvt_u32_f32_e32 v3, v3
	v_mul_lo_u32 v6, v6, v3
	v_mul_hi_u32 v6, v3, v6
	v_add_u32_e32 v3, v3, v6
	s_waitcnt vmcnt(0)
	v_mul_hi_u32 v3, v5, v3
	v_mul_lo_u32 v6, v3, v4
	v_sub_u32_e32 v6, v5, v6
	v_add_u32_e32 v7, 1, v3
	v_cmp_ge_u32_e32 vcc, v6, v4
	v_add_u32_e32 v5, 1, v5
	s_nop 0
	v_cndmask_b32_e32 v3, v3, v7, vcc
	v_sub_u32_e32 v7, v6, v4
	v_cndmask_b32_e32 v6, v6, v7, vcc
	v_add_u32_e32 v7, 1, v3
	v_cmp_ge_u32_e32 vcc, v6, v4
	s_nop 1
	v_cndmask_b32_e32 v3, v3, v7, vcc
	v_mul_lo_u32 v6, v4, v3
	v_add_u32_e32 v4, v6, v4
	v_cmp_ne_u32_e32 vcc, v5, v4
	s_and_saveexec_b64 s[6:7], vcc
	s_xor_b64 s[6:7], exec, s[6:7]
	s_cbranch_execz .LBB0_368
	s_waitcnt lgkmcnt(0)
	buffer_wbl2 sc1
	v_mov_b32_e32 v2, 0x2000
	global_load_dword v2, v2, s[4:5] offset:1024 sc1
	s_add_u32 s10, s4, 0x2400
	s_addc_u32 s11, s5, 0
	s_waitcnt vmcnt(0)
	v_cmp_eq_u32_e32 vcc, v2, v3
	s_and_saveexec_b64 s[8:9], vcc
	s_cbranch_execz .LBB0_367
	s_mov_b32 s26, 1
	s_mov_b64 s[12:13], 0
	v_mov_b32_e32 v2, 0
	s_branch .LBB0_358

.LBB0_1411:
	s_lshl_b32 s4, s97, 8
	s_add_u32 s4, s78, s4
	s_addc_u32 s5, s79, 0
	v_mov_b32_e32 v3, 0x1000
	v_mov_b32_e32 v5, 1
	global_atomic_add v5, v3, v5, s[4:5] offset:1024 sc0
	v_cvt_f32_u32_e32 v3, v4
	v_sub_u32_e32 v6, 0, v4
	v_rcp_iflag_f32_e32 v3, v3
	s_nop 0
	v_mul_f32_e32 v3, 0x4f7ffffe, v3
	v_cvt_u32_f32_e32 v3, v3
	v_mul_lo_u32 v6, v6, v3
	v_mul_hi_u32 v6, v3, v6
	v_add_u32_e32 v3, v3, v6
	s_waitcnt vmcnt(0)
	v_mul_hi_u32 v3, v5, v3
	v_mul_lo_u32 v6, v3, v4
	v_sub_u32_e32 v6, v5, v6
	v_add_u32_e32 v7, 1, v3
	v_cmp_ge_u32_e32 vcc, v6, v4
	v_add_u32_e32 v5, 1, v5
	s_nop 0
	v_cndmask_b32_e32 v3, v3, v7, vcc
	v_sub_u32_e32 v7, v6, v4
	v_cndmask_b32_e32 v6, v6, v7, vcc
	v_add_u32_e32 v7, 1, v3
	v_cmp_ge_u32_e32 vcc, v6, v4
	s_nop 1
	v_cndmask_b32_e32 v3, v3, v7, vcc
	v_mul_lo_u32 v6, v4, v3
	v_add_u32_e32 v4, v6, v4
	v_cmp_ne_u32_e32 vcc, v5, v4
	s_and_saveexec_b64 s[6:7], vcc
	s_xor_b64 s[6:7], exec, s[6:7]
	s_cbranch_execz .LBB0_1425
	s_waitcnt lgkmcnt(0)
	buffer_wbl2 sc1
	v_mov_b32_e32 v2, 0x2000
	global_load_dword v2, v2, s[4:5] offset:1024 sc1
	s_add_u32 s10, s4, 0x2400
	s_addc_u32 s11, s5, 0
	s_waitcnt vmcnt(0)
	v_cmp_eq_u32_e32 vcc, v2, v3
	s_and_saveexec_b64 s[8:9], vcc
	s_cbranch_execz .LBB0_1424
	s_mov_b32 s22, 1
	s_mov_b64 s[12:13], 0
	v_mov_b32_e32 v2, 0
	s_branch .LBB0_1415
